# v88 plus write-through (sc1) on the P0 conversion stores (W1A, W2A, XN)
# baseline (speedup 1.0000x reference)
.LBB0_32:
	s_waitcnt vmcnt(7)
	ds_write2_b32 v82, v36, v37 offset1:1
	ds_write2_b32 v82, v38, v39 offset0:2 offset1:3
	v_add_u32_e32 v36, 0x420, v82
	s_waitcnt vmcnt(6)
	ds_write2_b32 v36, v32, v33 offset1:1
	v_add_u32_e32 v32, 0x428, v82
	ds_write2_b32 v32, v34, v35 offset1:1
	v_add_u32_e32 v33, 0x840, v82
	v_add_u32_e32 v35, 0xc60, v82
	v_add_u32_e32 v37, 0xc68, v82
	s_waitcnt vmcnt(5)
	ds_write2_b32 v33, v44, v45 offset1:1
	v_add_u32_e32 v34, 0x848, v82
	s_waitcnt vmcnt(4)
	ds_write2_b32 v35, v40, v41 offset1:1
	ds_write2_b32 v37, v42, v43 offset1:1
	v_add_u32_e32 v38, 0x1080, v82
	v_add_u32_e32 v39, 0x1088, v82
	v_add_u32_e32 v40, 0x14a0, v82
	v_add_u32_e32 v41, 0x14a8, v82
	v_add_u32_e32 v42, 0x18c0, v82
	v_add_u32_e32 v43, 0x18c8, v82
	v_add_u32_e32 v44, 0x1ce0, v82
	v_add_u32_e32 v45, 0x1ce8, v82
	ds_write2_b32 v34, v46, v47 offset1:1
	s_waitcnt vmcnt(3)
	ds_write2_b32 v38, v52, v53 offset1:1
	ds_write2_b32 v39, v54, v55 offset1:1
	s_waitcnt vmcnt(2)
	ds_write2_b32 v40, v48, v49 offset1:1
	ds_write2_b32 v41, v50, v51 offset1:1
	s_waitcnt vmcnt(1)
	ds_write2_b32 v42, v60, v61 offset1:1
	ds_write2_b32 v43, v62, v63 offset1:1
	s_waitcnt vmcnt(0)
	ds_write2_b32 v44, v56, v57 offset1:1
	ds_write2_b32 v45, v58, v59 offset1:1
	s_waitcnt lgkmcnt(0)
	ds_read2_b32 v[50:51], v81 offset1:8
	ds_read2_b32 v[54:55], v81 offset0:33 offset1:41
	ds_read2_b32 v[56:57], v81 offset0:66 offset1:74
	ds_read2_b32 v[58:59], v81 offset0:99 offset1:107
	ds_read2_b32 v[60:61], v81 offset0:132 offset1:140
	s_waitcnt lgkmcnt(4)
	v_bfe_u32 v46, v50, 16, 1
	v_add3_u32 v46, v50, v46, s43
	s_waitcnt lgkmcnt(3)
	v_bfe_u32 v47, v54, 16, 1
	v_lshrrev_b32_e32 v46, 16, v46
	v_add3_u32 v47, v54, v47, s43
	ds_read2_b32 v[62:63], v81 offset0:165 offset1:173
	v_and_or_b32 v46, v47, s44, v46
	s_waitcnt lgkmcnt(3)
	v_bfe_u32 v47, v56, 16, 1
	v_add3_u32 v47, v56, v47, s43
	s_waitcnt lgkmcnt(2)
	v_bfe_u32 v48, v58, 16, 1
	ds_read2_b32 v[74:75], v81 offset0:198 offset1:206
	v_lshrrev_b32_e32 v47, 16, v47
	v_add3_u32 v48, v58, v48, s43
	ds_read2_b32 v[84:85], v81 offset0:231 offset1:239
	v_and_or_b32 v47, v48, s44, v47
	s_waitcnt lgkmcnt(3)
	v_bfe_u32 v48, v60, 16, 1
	v_add3_u32 v48, v60, v48, s43
	s_waitcnt lgkmcnt(2)
	v_bfe_u32 v49, v62, 16, 1
	v_lshrrev_b32_e32 v48, 16, v48
	v_add3_u32 v49, v62, v49, s43
	v_and_or_b32 v48, v49, s44, v48
	s_waitcnt lgkmcnt(1)
	v_bfe_u32 v49, v74, 16, 1
	v_add_u32_e32 v86, s49, v65
	s_ashr_i32 s19, s18, 31
	v_add3_u32 v49, v74, v49, s43
	s_waitcnt lgkmcnt(0)
	v_bfe_u32 v50, v84, 16, 1
	v_ashrrev_i32_e32 v87, 31, v86
	v_lshl_add_u64 v[52:53], s[18:19], 1, v[70:71]
	v_lshrrev_b32_e32 v49, 16, v49
	v_add3_u32 v50, v84, v50, s43
	v_lshlrev_b64 v[86:87], 12, v[86:87]
	v_and_or_b32 v49, v50, s44, v49
	v_lshl_add_u64 v[86:87], v[52:53], 0, v[86:87]
	global_store_dwordx4 v[86:87], v[46:49], off sc1
	v_bfe_u32 v50, v85, 16, 1
	v_add3_u32 v50, v85, v50, s43
	v_bfe_u32 v46, v51, 16, 1
	v_add3_u32 v46, v51, v46, s43
	v_bfe_u32 v47, v55, 16, 1
	v_lshrrev_b32_e32 v46, 16, v46
	v_add3_u32 v47, v55, v47, s43
	v_and_or_b32 v46, v47, s44, v46
	v_bfe_u32 v47, v57, 16, 1
	v_add3_u32 v47, v57, v47, s43
	v_bfe_u32 v48, v59, 16, 1
	v_lshrrev_b32_e32 v47, 16, v47
	v_add3_u32 v48, v59, v48, s43
	v_and_or_b32 v47, v48, s44, v47
	v_bfe_u32 v48, v61, 16, 1
	v_add3_u32 v48, v61, v48, s43
	v_bfe_u32 v49, v63, 16, 1
	v_lshrrev_b32_e32 v48, 16, v48
	v_add3_u32 v49, v63, v49, s43
	v_and_or_b32 v48, v49, s44, v48
	v_bfe_u32 v49, v75, 16, 1
	v_add3_u32 v49, v75, v49, s43
	v_lshrrev_b32_e32 v49, 16, v49
	v_and_or_b32 v49, v50, s44, v49
	v_add_u32_e32 v50, s49, v78
	v_ashrrev_i32_e32 v51, 31, v50
	v_lshlrev_b64 v[50:51], 12, v[50:51]
	ds_read2_b32 v[54:55], v81 offset0:16 offset1:24
	v_lshl_add_u64 v[50:51], v[52:53], 0, v[50:51]
	global_store_dwordx4 v[50:51], v[46:49], off sc1
	ds_read2_b32 v[50:51], v81 offset0:49 offset1:57
	ds_read2_b32 v[56:57], v81 offset0:82 offset1:90
	ds_read2_b32 v[58:59], v81 offset0:115 offset1:123
	s_waitcnt lgkmcnt(3)
	v_bfe_u32 v46, v54, 16, 1
	v_add3_u32 v46, v54, v46, s43
	s_waitcnt lgkmcnt(2)
	v_bfe_u32 v47, v50, 16, 1
	ds_read2_b32 v[60:61], v81 offset0:148 offset1:156
	v_lshrrev_b32_e32 v46, 16, v46
	v_add3_u32 v47, v50, v47, s43
	ds_read2_b32 v[62:63], v81 offset0:181 offset1:189
	v_and_or_b32 v46, v47, s44, v46
	s_waitcnt lgkmcnt(3)
	v_bfe_u32 v47, v56, 16, 1
	v_add3_u32 v47, v56, v47, s43
	s_waitcnt lgkmcnt(2)
	v_bfe_u32 v48, v58, 16, 1
	ds_read2_b32 v[74:75], v81 offset0:214 offset1:222
	v_lshrrev_b32_e32 v47, 16, v47
	v_add3_u32 v48, v58, v48, s43
	ds_read2_b32 v[84:85], v81 offset0:247 offset1:255
	v_and_or_b32 v47, v48, s44, v47
	s_waitcnt lgkmcnt(3)
	v_bfe_u32 v48, v60, 16, 1
	v_add3_u32 v48, v60, v48, s43
	s_waitcnt lgkmcnt(2)
	v_bfe_u32 v49, v62, 16, 1
	v_lshrrev_b32_e32 v48, 16, v48
	v_add3_u32 v49, v62, v49, s43
	v_and_or_b32 v48, v49, s44, v48
	s_waitcnt lgkmcnt(1)
	v_bfe_u32 v49, v74, 16, 1
	v_add_u32_e32 v86, s49, v79
	v_add3_u32 v49, v74, v49, s43
	s_waitcnt lgkmcnt(0)
	v_bfe_u32 v50, v84, 16, 1
	v_ashrrev_i32_e32 v87, 31, v86
	v_lshrrev_b32_e32 v49, 16, v49
	v_add3_u32 v50, v84, v50, s43
	v_lshlrev_b64 v[86:87], 12, v[86:87]
	v_and_or_b32 v49, v50, s44, v49
	v_lshl_add_u64 v[86:87], v[52:53], 0, v[86:87]
	global_store_dwordx4 v[86:87], v[46:49], off sc1
	v_bfe_u32 v50, v85, 16, 1
	v_add3_u32 v50, v85, v50, s43
	v_bfe_u32 v46, v55, 16, 1
	v_add3_u32 v46, v55, v46, s43
	v_bfe_u32 v47, v51, 16, 1
	v_lshrrev_b32_e32 v46, 16, v46
	v_add3_u32 v47, v51, v47, s43
	v_and_or_b32 v46, v47, s44, v46
	v_bfe_u32 v47, v57, 16, 1
	v_add3_u32 v47, v57, v47, s43
	v_bfe_u32 v48, v59, 16, 1
	v_lshrrev_b32_e32 v47, 16, v47
	v_add3_u32 v48, v59, v48, s43
	v_and_or_b32 v47, v48, s44, v47
	v_bfe_u32 v48, v61, 16, 1
	v_add3_u32 v48, v61, v48, s43
	v_bfe_u32 v49, v63, 16, 1
	v_lshrrev_b32_e32 v48, 16, v48
	v_add3_u32 v49, v63, v49, s43
	v_and_or_b32 v48, v49, s44, v48
	v_bfe_u32 v49, v75, 16, 1
	v_add3_u32 v49, v75, v49, s43
	v_lshrrev_b32_e32 v49, 16, v49
	v_and_or_b32 v49, v50, s44, v49
	v_add_u32_e32 v50, s49, v80
	v_ashrrev_i32_e32 v51, 31, v50
	v_lshlrev_b64 v[50:51], 12, v[50:51]
	v_lshl_add_u64 v[50:51], v[52:53], 0, v[50:51]
	global_store_dwordx4 v[50:51], v[46:49], off sc1
	s_waitcnt lgkmcnt(0)
	s_andn2_b64 vcc, exec, s[20:21]
	s_cbranch_vccnz .LBB0_22
	s_lshr_b32 s18, s48, 31
	s_ashr_i32 s21, s48, 6
	s_add_i32 s21, s21, s18
	s_mul_i32 s18, s21, 0x160
	s_sub_i32 s18, s23, s18
	s_lshl_b32 s22, s18, 5
	s_lshl_b32 s23, s18, 6
	s_cmpk_lt_i32 s18, 0xb0
	s_mov_b64 s[18:19], -1
	s_cbranch_scc1 .LBB0_35
	s_add_i32 s18, s23, 0x7fffd400
	s_and_b32 s18, s18, 0x7fffff00
	s_and_b32 s19, s22, 0x60
	s_or_b32 s18, s19, s18
	s_or_b32 s20, s18, 0x80
	s_mov_b64 s[18:19], 0

.LBB0_38:
	ds_write2_b32 v82, v0, v1 offset1:1
	ds_write2_b32 v82, v2, v3 offset0:2 offset1:3
	ds_write2_b32 v36, v4, v5 offset1:1
	ds_write2_b32 v32, v6, v7 offset1:1
	ds_write2_b32 v33, v8, v9 offset1:1
	ds_write2_b32 v34, v10, v11 offset1:1
	ds_write2_b32 v35, v12, v13 offset1:1
	ds_write2_b32 v37, v14, v15 offset1:1
	ds_write2_b32 v38, v16, v17 offset1:1
	ds_write2_b32 v39, v18, v19 offset1:1
	ds_write2_b32 v40, v20, v21 offset1:1
	ds_write2_b32 v41, v22, v23 offset1:1
	ds_write2_b32 v42, v24, v25 offset1:1
	ds_write2_b32 v43, v26, v27 offset1:1
	ds_write2_b32 v44, v28, v29 offset1:1
	ds_write2_b32 v45, v30, v31 offset1:1
	s_waitcnt lgkmcnt(0)
	ds_read2_b32 v[36:37], v81 offset1:8
	ds_read2_b32 v[40:41], v81 offset0:33 offset1:41
	ds_read2_b32 v[42:43], v81 offset0:66 offset1:74
	ds_read2_b32 v[44:45], v81 offset0:99 offset1:107
	ds_read2_b32 v[46:47], v81 offset0:132 offset1:140
	s_waitcnt lgkmcnt(4)
	v_bfe_u32 v32, v36, 16, 1
	v_add3_u32 v32, v36, v32, s39
	s_waitcnt lgkmcnt(3)
	v_bfe_u32 v33, v40, 16, 1
	v_lshrrev_b32_e32 v32, 16, v32
	v_add3_u32 v33, v40, v33, s39
	ds_read2_b32 v[48:49], v81 offset0:165 offset1:173
	v_and_or_b32 v32, v33, s40, v32
	s_waitcnt lgkmcnt(3)
	v_bfe_u32 v33, v42, 16, 1
	v_add3_u32 v33, v42, v33, s39
	s_waitcnt lgkmcnt(2)
	v_bfe_u32 v34, v44, 16, 1
	ds_read2_b32 v[50:51], v81 offset0:198 offset1:206
	v_lshrrev_b32_e32 v33, 16, v33
	v_add3_u32 v34, v44, v34, s39
	ds_read2_b32 v[52:53], v81 offset0:231 offset1:239
	v_and_or_b32 v33, v34, s40, v33
	s_waitcnt lgkmcnt(3)
	v_bfe_u32 v34, v46, 16, 1
	v_add3_u32 v34, v46, v34, s39
	s_waitcnt lgkmcnt(2)
	v_bfe_u32 v35, v48, 16, 1
	v_lshrrev_b32_e32 v34, 16, v34
	v_add3_u32 v35, v48, v35, s39
	s_lshl_b32 s6, s11, 6
	v_and_or_b32 v34, v35, s40, v34
	s_waitcnt lgkmcnt(1)
	v_bfe_u32 v35, v50, 16, 1
	v_add_u32_e32 v54, s10, v65
	s_ashr_i32 s7, s6, 31
	v_add3_u32 v35, v50, v35, s39
	s_waitcnt lgkmcnt(0)
	v_bfe_u32 v36, v52, 16, 1
	v_ashrrev_i32_e32 v55, 31, v54
	v_lshl_add_u64 v[38:39], s[6:7], 1, v[68:69]
	v_lshrrev_b32_e32 v35, 16, v35
	v_add3_u32 v36, v52, v36, s39
	v_lshlrev_b64 v[54:55], 12, v[54:55]
	v_and_or_b32 v35, v36, s40, v35
	v_lshl_add_u64 v[54:55], v[38:39], 0, v[54:55]
	global_store_dwordx4 v[54:55], v[32:35], off sc1
	v_bfe_u32 v36, v53, 16, 1
	v_add3_u32 v36, v53, v36, s39
	v_bfe_u32 v32, v37, 16, 1
	v_add3_u32 v32, v37, v32, s39
	v_bfe_u32 v33, v41, 16, 1
	v_lshrrev_b32_e32 v32, 16, v32
	v_add3_u32 v33, v41, v33, s39
	v_and_or_b32 v32, v33, s40, v32
	v_bfe_u32 v33, v43, 16, 1
	v_add3_u32 v33, v43, v33, s39
	v_bfe_u32 v34, v45, 16, 1
	v_lshrrev_b32_e32 v33, 16, v33
	v_add3_u32 v34, v45, v34, s39
	v_and_or_b32 v33, v34, s40, v33
	v_bfe_u32 v34, v47, 16, 1
	v_add3_u32 v34, v47, v34, s39
	v_bfe_u32 v35, v49, 16, 1
	v_lshrrev_b32_e32 v34, 16, v34
	v_add3_u32 v35, v49, v35, s39
	v_and_or_b32 v34, v35, s40, v34
	v_bfe_u32 v35, v51, 16, 1
	v_add3_u32 v35, v51, v35, s39
	v_lshrrev_b32_e32 v35, 16, v35
	v_and_or_b32 v35, v36, s40, v35
	v_add_u32_e32 v36, s10, v78
	v_ashrrev_i32_e32 v37, 31, v36
	v_lshlrev_b64 v[36:37], 12, v[36:37]
	ds_read2_b32 v[40:41], v81 offset0:16 offset1:24
	v_lshl_add_u64 v[36:37], v[38:39], 0, v[36:37]
	global_store_dwordx4 v[36:37], v[32:35], off sc1
	ds_read2_b32 v[36:37], v81 offset0:49 offset1:57
	ds_read2_b32 v[42:43], v81 offset0:82 offset1:90
	ds_read2_b32 v[44:45], v81 offset0:115 offset1:123
	s_waitcnt lgkmcnt(3)
	v_bfe_u32 v32, v40, 16, 1
	v_add3_u32 v32, v40, v32, s39
	s_waitcnt lgkmcnt(2)
	v_bfe_u32 v33, v36, 16, 1
	ds_read2_b32 v[46:47], v81 offset0:148 offset1:156
	v_lshrrev_b32_e32 v32, 16, v32
	v_add3_u32 v33, v36, v33, s39
	ds_read2_b32 v[48:49], v81 offset0:181 offset1:189
	v_and_or_b32 v32, v33, s40, v32
	s_waitcnt lgkmcnt(3)
	v_bfe_u32 v33, v42, 16, 1
	v_add3_u32 v33, v42, v33, s39
	s_waitcnt lgkmcnt(2)
	v_bfe_u32 v34, v44, 16, 1
	ds_read2_b32 v[50:51], v81 offset0:214 offset1:222
	v_lshrrev_b32_e32 v33, 16, v33
	v_add3_u32 v34, v44, v34, s39
	ds_read2_b32 v[52:53], v81 offset0:247 offset1:255
	v_and_or_b32 v33, v34, s40, v33
	s_waitcnt lgkmcnt(3)
	v_bfe_u32 v34, v46, 16, 1
	v_add3_u32 v34, v46, v34, s39
	s_waitcnt lgkmcnt(2)
	v_bfe_u32 v35, v48, 16, 1
	v_lshrrev_b32_e32 v34, 16, v34
	v_add3_u32 v35, v48, v35, s39
	v_and_or_b32 v34, v35, s40, v34
	s_waitcnt lgkmcnt(1)
	v_bfe_u32 v35, v50, 16, 1
	v_add_u32_e32 v54, s10, v79
	v_add3_u32 v35, v50, v35, s39
	s_waitcnt lgkmcnt(0)
	v_bfe_u32 v36, v52, 16, 1
	v_ashrrev_i32_e32 v55, 31, v54
	v_lshrrev_b32_e32 v35, 16, v35
	v_add3_u32 v36, v52, v36, s39
	v_lshlrev_b64 v[54:55], 12, v[54:55]
	v_and_or_b32 v35, v36, s40, v35
	v_lshl_add_u64 v[54:55], v[38:39], 0, v[54:55]
	global_store_dwordx4 v[54:55], v[32:35], off sc1
	v_bfe_u32 v36, v53, 16, 1
	v_add3_u32 v36, v53, v36, s39
	v_bfe_u32 v32, v41, 16, 1
	v_add3_u32 v32, v41, v32, s39
	v_bfe_u32 v33, v37, 16, 1
	v_lshrrev_b32_e32 v32, 16, v32
	v_add3_u32 v33, v37, v33, s39
	v_and_or_b32 v32, v33, s40, v32
	v_bfe_u32 v33, v43, 16, 1
	v_add3_u32 v33, v43, v33, s39
	v_bfe_u32 v34, v45, 16, 1
	v_lshrrev_b32_e32 v33, 16, v33
	v_add3_u32 v34, v45, v34, s39
	v_and_or_b32 v33, v34, s40, v33
	v_bfe_u32 v34, v47, 16, 1
	v_add3_u32 v34, v47, v34, s39
	v_bfe_u32 v35, v49, 16, 1
	v_lshrrev_b32_e32 v34, 16, v34
	v_add3_u32 v35, v49, v35, s39
	v_and_or_b32 v34, v35, s40, v34
	v_bfe_u32 v35, v51, 16, 1
	v_add3_u32 v35, v51, v35, s39
	v_lshrrev_b32_e32 v35, 16, v35
	v_and_or_b32 v35, v36, s40, v35
	v_add_u32_e32 v36, s10, v80
	v_ashrrev_i32_e32 v37, 31, v36
	v_lshlrev_b64 v[36:37], 12, v[36:37]
	v_lshl_add_u64 v[36:37], v[38:39], 0, v[36:37]
	global_store_dwordx4 v[36:37], v[32:35], off sc1
	s_waitcnt lgkmcnt(0)

.LBB0_49:
	s_waitcnt vmcnt(7)
	ds_write2_b32 v82, v36, v37 offset1:1
	ds_write2_b32 v82, v38, v39 offset0:2 offset1:3
	v_add_u32_e32 v36, 0x420, v82
	s_waitcnt vmcnt(6)
	ds_write2_b32 v36, v32, v33 offset1:1
	v_add_u32_e32 v32, 0x428, v82
	ds_write2_b32 v32, v34, v35 offset1:1
	v_add_u32_e32 v33, 0x840, v82
	v_add_u32_e32 v35, 0xc60, v82
	v_add_u32_e32 v37, 0xc68, v82
	s_waitcnt vmcnt(5)
	ds_write2_b32 v33, v44, v45 offset1:1
	v_add_u32_e32 v34, 0x848, v82
	s_waitcnt vmcnt(4)
	ds_write2_b32 v35, v40, v41 offset1:1
	ds_write2_b32 v37, v42, v43 offset1:1
	v_add_u32_e32 v38, 0x1080, v82
	v_add_u32_e32 v39, 0x1088, v82
	v_add_u32_e32 v40, 0x14a0, v82
	v_add_u32_e32 v41, 0x14a8, v82
	v_add_u32_e32 v42, 0x18c0, v82
	v_add_u32_e32 v43, 0x18c8, v82
	v_add_u32_e32 v44, 0x1ce0, v82
	v_add_u32_e32 v45, 0x1ce8, v82
	ds_write2_b32 v34, v46, v47 offset1:1
	s_waitcnt vmcnt(3)
	ds_write2_b32 v38, v52, v53 offset1:1
	ds_write2_b32 v39, v54, v55 offset1:1
	s_waitcnt vmcnt(2)
	ds_write2_b32 v40, v48, v49 offset1:1
	ds_write2_b32 v41, v50, v51 offset1:1
	s_waitcnt vmcnt(1)
	ds_write2_b32 v42, v60, v61 offset1:1
	ds_write2_b32 v43, v62, v63 offset1:1
	s_waitcnt vmcnt(0)
	ds_write2_b32 v44, v56, v57 offset1:1
	ds_write2_b32 v45, v58, v59 offset1:1
	s_waitcnt lgkmcnt(0)
	ds_read2_b32 v[50:51], v81 offset1:8
	ds_read2_b32 v[54:55], v81 offset0:33 offset1:41
	ds_read2_b32 v[56:57], v81 offset0:66 offset1:74
	ds_read2_b32 v[58:59], v81 offset0:99 offset1:107
	ds_read2_b32 v[60:61], v81 offset0:132 offset1:140
	s_waitcnt lgkmcnt(4)
	v_bfe_u32 v46, v50, 16, 1
	v_add3_u32 v46, v50, v46, s39
	s_waitcnt lgkmcnt(3)
	v_bfe_u32 v47, v54, 16, 1
	v_lshrrev_b32_e32 v46, 16, v46
	v_add3_u32 v47, v54, v47, s39
	ds_read2_b32 v[62:63], v81 offset0:165 offset1:173
	v_and_or_b32 v46, v47, s40, v46
	s_waitcnt lgkmcnt(3)
	v_bfe_u32 v47, v56, 16, 1
	v_add3_u32 v47, v56, v47, s39
	s_waitcnt lgkmcnt(2)
	v_bfe_u32 v48, v58, 16, 1
	ds_read2_b32 v[72:73], v81 offset0:198 offset1:206
	v_lshrrev_b32_e32 v47, 16, v47
	v_add3_u32 v48, v58, v48, s39
	ds_read2_b32 v[74:75], v81 offset0:231 offset1:239
	v_and_or_b32 v47, v48, s40, v47
	s_waitcnt lgkmcnt(3)
	v_bfe_u32 v48, v60, 16, 1
	v_add3_u32 v48, v60, v48, s39
	s_waitcnt lgkmcnt(2)
	v_bfe_u32 v49, v62, 16, 1
	v_lshrrev_b32_e32 v48, 16, v48
	v_add3_u32 v49, v62, v49, s39
	v_and_or_b32 v48, v49, s40, v48
	s_waitcnt lgkmcnt(1)
	v_bfe_u32 v49, v72, 16, 1
	v_add_u32_e32 v84, s43, v65
	s_ashr_i32 s7, s6, 31
	v_add3_u32 v49, v72, v49, s39
	s_waitcnt lgkmcnt(0)
	v_bfe_u32 v50, v74, 16, 1
	v_ashrrev_i32_e32 v85, 31, v84
	v_lshl_add_u64 v[52:53], s[6:7], 1, v[68:69]
	v_lshrrev_b32_e32 v49, 16, v49
	v_add3_u32 v50, v74, v50, s39
	v_lshlrev_b64 v[84:85], 12, v[84:85]
	v_and_or_b32 v49, v50, s40, v49
	v_lshl_add_u64 v[84:85], v[52:53], 0, v[84:85]
	global_store_dwordx4 v[84:85], v[46:49], off sc1
	v_bfe_u32 v50, v75, 16, 1
	v_add3_u32 v50, v75, v50, s39
	v_bfe_u32 v46, v51, 16, 1
	v_add3_u32 v46, v51, v46, s39
	v_bfe_u32 v47, v55, 16, 1
	v_lshrrev_b32_e32 v46, 16, v46
	v_add3_u32 v47, v55, v47, s39
	v_and_or_b32 v46, v47, s40, v46
	v_bfe_u32 v47, v57, 16, 1
	v_add3_u32 v47, v57, v47, s39
	v_bfe_u32 v48, v59, 16, 1
	v_lshrrev_b32_e32 v47, 16, v47
	v_add3_u32 v48, v59, v48, s39
	v_and_or_b32 v47, v48, s40, v47
	v_bfe_u32 v48, v61, 16, 1
	v_add3_u32 v48, v61, v48, s39
	v_bfe_u32 v49, v63, 16, 1
	v_lshrrev_b32_e32 v48, 16, v48
	v_add3_u32 v49, v63, v49, s39
	v_and_or_b32 v48, v49, s40, v48
	v_bfe_u32 v49, v73, 16, 1
	v_add3_u32 v49, v73, v49, s39
	v_lshrrev_b32_e32 v49, 16, v49
	v_and_or_b32 v49, v50, s40, v49
	v_add_u32_e32 v50, s43, v78
	v_ashrrev_i32_e32 v51, 31, v50
	v_lshlrev_b64 v[50:51], 12, v[50:51]
	ds_read2_b32 v[54:55], v81 offset0:16 offset1:24
	v_lshl_add_u64 v[50:51], v[52:53], 0, v[50:51]
	global_store_dwordx4 v[50:51], v[46:49], off sc1
	ds_read2_b32 v[50:51], v81 offset0:49 offset1:57
	ds_read2_b32 v[56:57], v81 offset0:82 offset1:90
	ds_read2_b32 v[58:59], v81 offset0:115 offset1:123
	s_waitcnt lgkmcnt(3)
	v_bfe_u32 v46, v54, 16, 1
	v_add3_u32 v46, v54, v46, s39
	s_waitcnt lgkmcnt(2)
	v_bfe_u32 v47, v50, 16, 1
	ds_read2_b32 v[60:61], v81 offset0:148 offset1:156
	v_lshrrev_b32_e32 v46, 16, v46
	v_add3_u32 v47, v50, v47, s39
	ds_read2_b32 v[62:63], v81 offset0:181 offset1:189
	v_and_or_b32 v46, v47, s40, v46
	s_waitcnt lgkmcnt(3)
	v_bfe_u32 v47, v56, 16, 1
	v_add3_u32 v47, v56, v47, s39
	s_waitcnt lgkmcnt(2)
	v_bfe_u32 v48, v58, 16, 1
	ds_read2_b32 v[72:73], v81 offset0:214 offset1:222
	v_lshrrev_b32_e32 v47, 16, v47
	v_add3_u32 v48, v58, v48, s39
	ds_read2_b32 v[74:75], v81 offset0:247 offset1:255
	v_and_or_b32 v47, v48, s40, v47
	s_waitcnt lgkmcnt(3)
	v_bfe_u32 v48, v60, 16, 1
	v_add3_u32 v48, v60, v48, s39
	s_waitcnt lgkmcnt(2)
	v_bfe_u32 v49, v62, 16, 1
	v_lshrrev_b32_e32 v48, 16, v48
	v_add3_u32 v49, v62, v49, s39
	v_and_or_b32 v48, v49, s40, v48
	s_waitcnt lgkmcnt(1)
	v_bfe_u32 v49, v72, 16, 1
	v_add_u32_e32 v84, s43, v79
	v_add3_u32 v49, v72, v49, s39
	s_waitcnt lgkmcnt(0)
	v_bfe_u32 v50, v74, 16, 1
	v_ashrrev_i32_e32 v85, 31, v84
	v_lshrrev_b32_e32 v49, 16, v49
	v_add3_u32 v50, v74, v50, s39
	v_lshlrev_b64 v[84:85], 12, v[84:85]
	v_and_or_b32 v49, v50, s40, v49
	v_lshl_add_u64 v[84:85], v[52:53], 0, v[84:85]
	global_store_dwordx4 v[84:85], v[46:49], off sc1
	v_bfe_u32 v50, v75, 16, 1
	v_add3_u32 v50, v75, v50, s39
	v_bfe_u32 v46, v55, 16, 1
	v_add3_u32 v46, v55, v46, s39
	v_bfe_u32 v47, v51, 16, 1
	v_lshrrev_b32_e32 v46, 16, v46
	v_add3_u32 v47, v51, v47, s39
	v_and_or_b32 v46, v47, s40, v46
	v_bfe_u32 v47, v57, 16, 1
	v_add3_u32 v47, v57, v47, s39
	v_bfe_u32 v48, v59, 16, 1
	v_lshrrev_b32_e32 v47, 16, v47
	v_add3_u32 v48, v59, v48, s39
	v_and_or_b32 v47, v48, s40, v47
	v_bfe_u32 v48, v61, 16, 1
	v_add3_u32 v48, v61, v48, s39
	v_bfe_u32 v49, v63, 16, 1
	v_lshrrev_b32_e32 v48, 16, v48
	v_add3_u32 v49, v63, v49, s39
	v_and_or_b32 v48, v49, s40, v48
	v_bfe_u32 v49, v73, 16, 1
	v_add3_u32 v49, v73, v49, s39
	v_lshrrev_b32_e32 v49, 16, v49
	v_and_or_b32 v49, v50, s40, v49
	v_add_u32_e32 v50, s43, v80
	v_ashrrev_i32_e32 v51, 31, v50
	v_lshlrev_b64 v[50:51], 12, v[50:51]
	v_lshl_add_u64 v[50:51], v[52:53], 0, v[50:51]
	global_store_dwordx4 v[50:51], v[46:49], off sc1
	s_waitcnt lgkmcnt(0)
	s_andn2_b64 vcc, exec, s[10:11]
	s_cbranch_vccnz .LBB0_39
	s_lshr_b32 s6, s42, 31
	s_ashr_i32 s11, s42, 6
	s_add_i32 s11, s11, s6
	s_mul_i32 s6, s11, 0x160
	s_sub_i32 s6, s19, s6
	s_lshl_b32 s18, s6, 5
	s_lshl_b32 s19, s6, 6
	s_cmpk_lt_i32 s6, 0xb0
	s_mov_b64 s[6:7], -1
	s_cbranch_scc1 .LBB0_52
	s_add_i32 s6, s19, 0x7fffd400
	s_and_b32 s6, s6, 0x7fffff00
	s_and_b32 s7, s18, 0x60
	s_or_b32 s6, s7, s6
	s_or_b32 s10, s6, 0x80
	s_mov_b64 s[6:7], 0

.LBB0_56:
	s_or_b64 exec, exec, s[12:13]
	v_bfe_u32 v43, v28, 16, 1
	v_add3_u32 v28, v28, v43, s18
	v_bfe_u32 v43, v29, 16, 1
	v_lshrrev_b32_e32 v28, 16, v28
	v_add3_u32 v29, v29, v43, s18
	v_and_or_b32 v28, v29, s19, v28
	v_bfe_u32 v29, v30, 16, 1
	v_add3_u32 v29, v30, v29, s18
	v_bfe_u32 v30, v31, 16, 1
	s_waitcnt lgkmcnt(0)
	v_lshl_add_u64 v[44:45], s[26:27], 0, v[32:33]
	v_lshrrev_b32_e32 v29, 16, v29
	v_add3_u32 v30, v31, v30, s18
	v_and_or_b32 v29, v30, s19, v29
	v_add_co_u32_e32 v30, vcc, s20, v44
	s_add_i32 s21, s21, s62
	s_nop 0
	v_addc_co_u32_e32 v31, vcc, 0, v45, vcc
	global_store_dwordx2 v[30:31], v[28:29], off sc1
	v_bfe_u32 v28, v24, 16, 1
	v_add3_u32 v24, v24, v28, s18
	v_bfe_u32 v28, v25, 16, 1
	v_lshrrev_b32_e32 v24, 16, v24
	v_add3_u32 v25, v25, v28, s18
	v_and_or_b32 v24, v25, s19, v24
	v_bfe_u32 v25, v26, 16, 1
	v_add3_u32 v25, v26, v25, s18
	v_bfe_u32 v26, v27, 16, 1
	v_lshrrev_b32_e32 v25, 16, v25
	v_add3_u32 v26, v27, v26, s18
	v_and_or_b32 v25, v26, s19, v25
	global_store_dwordx2 v[30:31], v[24:25], off offset:512 sc1
	v_bfe_u32 v24, v20, 16, 1
	v_add3_u32 v20, v20, v24, s18
	v_bfe_u32 v24, v21, 16, 1
	v_lshrrev_b32_e32 v20, 16, v20
	v_add3_u32 v21, v21, v24, s18
	v_and_or_b32 v20, v21, s19, v20
	v_bfe_u32 v21, v22, 16, 1
	v_add3_u32 v21, v22, v21, s18
	v_bfe_u32 v22, v23, 16, 1
	v_lshrrev_b32_e32 v21, 16, v21
	v_add3_u32 v22, v23, v22, s18
	v_and_or_b32 v21, v22, s19, v21
	global_store_dwordx2 v[30:31], v[20:21], off offset:1024 sc1
	v_bfe_u32 v20, v16, 16, 1
	v_add3_u32 v16, v16, v20, s18
	v_bfe_u32 v20, v17, 16, 1
	v_lshrrev_b32_e32 v16, 16, v16
	v_add3_u32 v17, v17, v20, s18
	v_and_or_b32 v16, v17, s19, v16
	v_bfe_u32 v17, v18, 16, 1
	v_add3_u32 v17, v18, v17, s18
	v_bfe_u32 v18, v19, 16, 1
	v_lshrrev_b32_e32 v17, 16, v17
	v_add3_u32 v18, v19, v18, s18
	v_and_or_b32 v17, v18, s19, v17
	global_store_dwordx2 v[30:31], v[16:17], off offset:1536 sc1
	v_bfe_u32 v16, v12, 16, 1
	v_add3_u32 v12, v12, v16, s18
	v_bfe_u32 v16, v13, 16, 1
	v_lshrrev_b32_e32 v12, 16, v12
	v_add3_u32 v13, v13, v16, s18
	v_and_or_b32 v12, v13, s19, v12
	v_bfe_u32 v13, v14, 16, 1
	v_add3_u32 v13, v14, v13, s18
	v_bfe_u32 v14, v15, 16, 1
	v_lshrrev_b32_e32 v13, 16, v13
	v_add3_u32 v14, v15, v14, s18
	v_and_or_b32 v13, v14, s19, v13
	global_store_dwordx2 v[30:31], v[12:13], off offset:2048 sc1
	v_bfe_u32 v12, v8, 16, 1
	v_add3_u32 v8, v8, v12, s18
	v_bfe_u32 v12, v9, 16, 1
	v_lshrrev_b32_e32 v8, 16, v8
	v_add3_u32 v9, v9, v12, s18
	v_and_or_b32 v8, v9, s19, v8
	v_bfe_u32 v9, v10, 16, 1
	v_add3_u32 v9, v10, v9, s18
	v_bfe_u32 v10, v11, 16, 1
	v_lshrrev_b32_e32 v9, 16, v9
	v_add3_u32 v10, v11, v10, s18
	v_and_or_b32 v9, v10, s19, v9
	global_store_dwordx2 v[30:31], v[8:9], off offset:2560 sc1
	v_bfe_u32 v8, v4, 16, 1
	v_add3_u32 v4, v4, v8, s18
	v_bfe_u32 v8, v5, 16, 1
	v_lshrrev_b32_e32 v4, 16, v4
	v_add3_u32 v5, v5, v8, s18
	v_and_or_b32 v4, v5, s19, v4
	v_bfe_u32 v5, v6, 16, 1
	v_add3_u32 v5, v6, v5, s18
	v_bfe_u32 v6, v7, 16, 1
	v_lshrrev_b32_e32 v5, 16, v5
	v_add3_u32 v6, v7, v6, s18
	v_and_or_b32 v5, v6, s19, v5
	global_store_dwordx2 v[30:31], v[4:5], off offset:3072 sc1
	v_bfe_u32 v4, v0, 16, 1
	v_add3_u32 v0, v0, v4, s18
	v_bfe_u32 v4, v1, 16, 1
	v_lshrrev_b32_e32 v0, 16, v0
	v_add3_u32 v1, v1, v4, s18
	v_and_or_b32 v0, v1, s19, v0
	v_bfe_u32 v1, v2, 16, 1
	v_add3_u32 v1, v2, v1, s18
	v_bfe_u32 v2, v3, 16, 1
	s_add_u32 s14, s14, s6
	v_lshrrev_b32_e32 v1, 16, v1
	v_add3_u32 v2, v3, v2, s18
	s_addc_u32 s15, s15, s7
	v_and_or_b32 v1, v2, s19, v1
	v_lshl_add_u64 v[32:33], v[32:33], 0, s[10:11]
	s_cmpk_gt_i32 s21, 0x1fff
	v_lshl_add_u64 v[34:35], v[34:35], 0, s[8:9]
	global_store_dwordx2 v[30:31], v[0:1], off offset:3584 sc1
	s_cbranch_scc1 .LBB0_59
